# P9: prefetch residual base tile toward L2/MALL during the K loop (4 dword loads per wave)
# baseline (speedup 1.0000x reference)
.Lp9_noswap:
	s_lshl_b32 s56, s98, 6
	s_branch .LBB0_2089

.LBB0_2088:
	v_readlane_b32 s64, v254, 54
	s_mov_b32 s34, s64
	s_add_i32 s82, s82, s98
	s_add_i32 s6, s6, s98
	s_add_i32 s33, s33, s56
	s_and_b64 vcc, exec, s[62:63]
	s_mov_b32 s84, s83
	v_readlane_b32 s65, v254, 55
	s_cbranch_vccnz .LBB0_2125

.LBB0_2115:
	v_mov_b32_e32 v8, v250
	s_ashr_i32 s8, s8, 3
	v_bfe_i32 v1, v8, 27, 1
	v_lshlrev_b32_e32 v4, 4, v8
	v_lshrrev_b32_e32 v1, 22, v1
	v_add_u32_e32 v1, v4, v1
	v_and_b32_e32 v1, 0xfffffc00, v1
	v_ashrrev_i32_e32 v0, 31, v8
	v_sub_u32_e32 v1, v4, v1
	v_lshrrev_b32_e32 v0, 26, v0
	v_lshrrev_b32_e32 v2, 4, v1
	v_add_u32_e32 v0, v8, v0
	v_bitop3_b32 v3, v2, v1, 32 bitop3:0x6c
	v_ashrrev_i32_e32 v1, 31, v1
	v_ashrrev_i32_e32 v0, 6, v0
	v_lshrrev_b32_e32 v1, 26, v1
	v_lshlrev_b32_e32 v2, 3, v0
	v_add_u32_e32 v1, v3, v1
	s_add_i32 s8, s71, s8
	v_and_b32_e32 v2, 0x1ffff0, v2
	v_ashrrev_i32_e32 v1, 6, v1
	s_ashr_i32 s68, s8, 31
	v_add_u32_e32 v5, v1, v2
	v_lshlrev_b32_e32 v2, 5, v0
	v_mul_i32_i24_e32 v6, 64, v1
	s_lshr_b32 s68, s68, 26
	v_and_b32_e32 v2, 32, v2
	v_sub_u32_e32 v3, v3, v6
	s_add_i32 s68, s8, s68
	v_ashrrev_i16_sdwa v3, v148, sext(v3) dst_sel:DWORD dst_unused:UNUSED_PAD src0_sel:DWORD src1_sel:BYTE_0
	v_lshl_or_b32 v5, v5, 11, v2
	s_ashr_i32 s69, s68, 6
	s_and_b32 s68, s68, 0xffc0
	v_add_u32_sdwa v134, v5, sext(v3) dst_sel:DWORD dst_unused:UNUSED_PAD src0_sel:DWORD src1_sel:WORD_0
	v_add_u32_e32 v5, 0x2000, v4
	s_sub_i32 s68, s8, s68
	v_ashrrev_i32_e32 v4, 31, v5
	s_bfe_i32 s8, s68, 0x80000
	v_lshrrev_b32_e32 v4, 22, v4
	s_bfe_u32 s8, s8, 0x3000c
	v_add_u32_e32 v4, v5, v4
	s_add_i32 s70, s68, s8
	v_ashrrev_i32_e32 v4, 10, v4
	s_bfe_i32 s8, s70, 0x80000
	s_and_b32 s70, s70, 0xf8
	v_mul_i32_i24_e32 v6, 0x400, v4
	s_sub_i32 s68, s68, s70
	v_sub_u32_e32 v5, v5, v6
	s_lshl_b32 s69, s69, 3
	s_sext_i32_i8 s68, s68
	v_lshrrev_b32_e32 v6, 4, v5
	s_add_i32 s68, s69, s68
	v_bitop3_b32 v7, v6, v5, 32 bitop3:0x6c
	v_lshlrev_b32_e32 v5, 3, v4
	s_sext_i32_i16 s8, s8
	s_ashr_i32 s69, s68, 31
	v_and_b32_e32 v6, 0x1ffff0, v5
	v_ashrrev_i32_e32 v5, 31, v7
	s_lshr_b32 s8, s8, 3
	s_lshl_b64 s[72:73], s[68:69], 20
	v_lshrrev_b32_e32 v5, 26, v5
	s_add_u32 s70, s0, s72
	v_add_u32_e32 v9, v7, v5
	s_addc_u32 s71, s1, s73
	s_bfe_i64 s[74:75], s[8:9], 0x100000
	v_ashrrev_i32_e32 v5, 6, v9
	s_lshl_b64 s[74:75], s[74:75], 20
	v_add_u32_e32 v10, v5, v6
	v_lshlrev_b32_e32 v6, 5, v4
	v_and_b32_e32 v9, 0xc0, v9
	s_add_u32 s76, s2, s74
	v_readfirstlane_b32 s69, v8
	v_and_b32_e32 v6, 32, v6
	v_sub_u32_e32 v7, v7, v9
	s_addc_u32 s77, s7, s75
	s_ashr_i32 s85, s69, 6
	v_ashrrev_i16_sdwa v7, v148, sext(v7) dst_sel:DWORD dst_unused:UNUSED_PAD src0_sel:DWORD src1_sel:BYTE_0
	v_lshl_or_b32 v9, v10, 11, v6
	s_lshl_b32 s86, s85, 10
	v_readlane_b32 s88, v254, 50
	v_add_u32_sdwa v136, v9, sext(v7) dst_sel:DWORD dst_unused:UNUSED_PAD src0_sel:DWORD src1_sel:WORD_0
	s_lshl_b32 s100, s68, 21
	s_lshl_b32 s101, s8, 10
	s_add_u32 s100, s100, s101
	s_add_u32 s100, s14, s100
	s_addc_u32 s101, s15, 0
	v_and_b32_e32 v10, 63, v8
	v_lshl_or_b32 v10, s85, 8, v10
	v_lshrrev_b32_e32 v12, 3, v10
	v_and_b32_e32 v13, 7, v10
	v_lshlrev_b32_e32 v12, 13, v12
	v_lshl_or_b32 v12, v13, 7, v12
	global_load_dword v120, v12, s[100:101]
	v_add_u32_e32 v11, 64, v10
	v_lshrrev_b32_e32 v12, 3, v11
	v_and_b32_e32 v13, 7, v11
	v_lshlrev_b32_e32 v12, 13, v12
	v_lshl_or_b32 v12, v13, 7, v12
	global_load_dword v121, v12, s[100:101]
	v_add_u32_e32 v11, 0x80, v10
	v_lshrrev_b32_e32 v12, 3, v11
	v_and_b32_e32 v13, 7, v11
	v_lshlrev_b32_e32 v12, 13, v12
	v_lshl_or_b32 v12, v13, 7, v12
	global_load_dword v122, v12, s[100:101]
	v_add_u32_e32 v11, 0xc0, v10
	v_lshrrev_b32_e32 v12, 3, v11
	v_and_b32_e32 v13, 7, v11
	v_lshlrev_b32_e32 v12, 13, v12
	v_lshl_or_b32 v12, v13, 7, v12
	global_load_dword v123, v12, s[100:101]
	s_cmp_lg_u32 s84, s99
	v_ashrrev_i32_e32 v135, 31, v134
	v_ashrrev_i32_e32 v137, 31, v136
	v_readlane_b32 s89, v254, 51
	s_cbranch_scc1 .LBB0_2117
	s_add_i32 s84, s86, 32
	v_lshlrev_b64 v[10:11], 1, v[134:135]
	s_add_i32 m0, s84, 0x10000
	v_lshl_add_u64 v[12:13], s[76:77], 0, v[10:11]
	global_load_lds_dwordx4 v[12:13], off
	v_lshlrev_b64 v[12:13], 1, v[136:137]
	v_lshl_add_u64 v[14:15], s[76:77], 0, v[12:13]
	s_add_i32 m0, s84, 0x12000
	s_nop 0
	global_load_lds_dwordx4 v[14:15], off
	v_lshl_add_u64 v[14:15], s[70:71], 0, v[10:11]
	s_mov_b32 m0, s84
	s_nop 0
	global_load_lds_dwordx4 v[14:15], off
	s_add_i32 m0, s84, 0x2000
	s_add_u32 s88, s76, 0x80000
	v_lshl_add_u64 v[14:15], s[70:71], 0, v[12:13]
	s_addc_u32 s89, s77, 0
	global_load_lds_dwordx4 v[14:15], off
	s_add_i32 m0, s84, 0x14000
	v_lshl_add_u64 v[14:15], s[88:89], 0, v[10:11]
	global_load_lds_dwordx4 v[14:15], off
	s_add_i32 m0, s84, 0x16000
	v_lshl_add_u64 v[14:15], s[88:89], 0, v[12:13]
	s_add_u32 s88, s70, 0x80000
	s_addc_u32 s89, s71, 0
	global_load_lds_dwordx4 v[14:15], off
	s_add_i32 m0, s84, 0x4000
	v_lshl_add_u64 v[10:11], s[88:89], 0, v[10:11]
	global_load_lds_dwordx4 v[10:11], off
	v_lshl_add_u64 v[10:11], s[88:89], 0, v[12:13]
	s_add_i32 m0, s84, 0x6000
	s_nop 0
	global_load_lds_dwordx4 v[10:11], off
